# c24 + every v_pk_mul_f32 in the two attention phases (rescale blocks, epilogues) split into two v_mul_f32
# baseline (speedup 1.0000x reference)
.Lresc_mla_odd_blk:
	s_and_saveexec_b64 s[60:61], s[4:5]
	ds_write_b32 v233, v240 offset:128
	s_or_b64 exec, exec, s[60:61]
	s_waitcnt lgkmcnt(0)
	ds_read_b128 v[2:5], v232 offset:224
	ds_read_b128 v[6:9], v232 offset:192
	ds_read_b128 v[10:13], v232 offset:160
	ds_read_b128 v[112:115], v232 offset:128
	s_waitcnt lgkmcnt(0)
	v_mul_f32_e32 v78, v78, v4
	v_mul_f32_e32 v79, v79, v5
	v_mul_f32_e32 v74, v74, v8
	v_mul_f32_e32 v75, v75, v9
	v_mul_f32_e32 v70, v70, v12
	v_mul_f32_e32 v71, v71, v13
	v_mul_f32_e32 v66, v66, v114
	v_mul_f32_e32 v67, v67, v115
	v_mul_f32_e32 v76, v76, v2
	v_mul_f32_e32 v77, v77, v3
	v_mul_f32_e32 v72, v72, v6
	v_mul_f32_e32 v73, v73, v7
	v_mul_f32_e32 v68, v68, v10
	v_mul_f32_e32 v69, v69, v11
	v_mul_f32_e32 v64, v64, v112
	v_mul_f32_e32 v65, v65, v113
	v_mul_f32_e32 v62, v62, v4
	v_mul_f32_e32 v63, v63, v5
	v_mul_f32_e32 v58, v58, v8
	v_mul_f32_e32 v59, v59, v9
	v_mul_f32_e32 v54, v54, v12
	v_mul_f32_e32 v55, v55, v13
	v_mul_f32_e32 v50, v50, v114
	v_mul_f32_e32 v51, v51, v115
	v_mul_f32_e32 v60, v60, v2
	v_mul_f32_e32 v61, v61, v3
	v_mul_f32_e32 v56, v56, v6
	v_mul_f32_e32 v57, v57, v7
	v_mul_f32_e32 v52, v52, v10
	v_mul_f32_e32 v53, v53, v11
	v_mul_f32_e32 v48, v48, v112
	v_mul_f32_e32 v49, v49, v113
	v_mul_f32_e32 v46, v46, v4
	v_mul_f32_e32 v47, v47, v5
	v_mul_f32_e32 v42, v42, v8
	v_mul_f32_e32 v43, v43, v9
	v_mul_f32_e32 v38, v38, v12
	v_mul_f32_e32 v39, v39, v13
	v_mul_f32_e32 v34, v34, v114
	v_mul_f32_e32 v35, v35, v115
	v_mul_f32_e32 v44, v44, v2
	v_mul_f32_e32 v45, v45, v3
	v_mul_f32_e32 v40, v40, v6
	v_mul_f32_e32 v41, v41, v7
	v_mul_f32_e32 v36, v36, v10
	v_mul_f32_e32 v37, v37, v11
	v_mul_f32_e32 v32, v32, v112
	v_mul_f32_e32 v33, v33, v113
	v_mul_f32_e32 v30, v30, v4
	v_mul_f32_e32 v31, v31, v5
	v_mul_f32_e32 v26, v26, v8
	v_mul_f32_e32 v27, v27, v9
	v_mul_f32_e32 v22, v22, v12
	v_mul_f32_e32 v23, v23, v13
	v_mul_f32_e32 v18, v18, v114
	v_mul_f32_e32 v19, v19, v115
	v_mul_f32_e32 v28, v28, v2
	v_mul_f32_e32 v29, v29, v3
	v_mul_f32_e32 v24, v24, v6
	v_mul_f32_e32 v25, v25, v7
	v_mul_f32_e32 v20, v20, v10
	v_mul_f32_e32 v21, v21, v11
	v_mul_f32_e32 v16, v16, v112
	v_mul_f32_e32 v17, v17, v113
	s_branch .LBB0_876

.Lresc_mla_even_blk:
	s_and_saveexec_b64 s[60:61], s[4:5]
	ds_write_b32 v233, v0 offset:128
	s_or_b64 exec, exec, s[60:61]
	s_waitcnt lgkmcnt(0)
	ds_read_b128 v[2:5], v232 offset:224
	ds_read_b128 v[6:9], v232 offset:192
	ds_read_b128 v[10:13], v232 offset:160
	ds_read_b128 v[112:115], v232 offset:128
	s_waitcnt lgkmcnt(0)
	v_mul_f32_e32 v78, v78, v4
	v_mul_f32_e32 v79, v79, v5
	v_mul_f32_e32 v74, v74, v8
	v_mul_f32_e32 v75, v75, v9
	v_mul_f32_e32 v70, v70, v12
	v_mul_f32_e32 v71, v71, v13
	v_mul_f32_e32 v66, v66, v114
	v_mul_f32_e32 v67, v67, v115
	v_mul_f32_e32 v76, v76, v2
	v_mul_f32_e32 v77, v77, v3
	v_mul_f32_e32 v72, v72, v6
	v_mul_f32_e32 v73, v73, v7
	v_mul_f32_e32 v68, v68, v10
	v_mul_f32_e32 v69, v69, v11
	v_mul_f32_e32 v64, v64, v112
	v_mul_f32_e32 v65, v65, v113
	v_mul_f32_e32 v62, v62, v4
	v_mul_f32_e32 v63, v63, v5
	v_mul_f32_e32 v58, v58, v8
	v_mul_f32_e32 v59, v59, v9
	v_mul_f32_e32 v54, v54, v12
	v_mul_f32_e32 v55, v55, v13
	v_mul_f32_e32 v50, v50, v114
	v_mul_f32_e32 v51, v51, v115
	v_mul_f32_e32 v60, v60, v2
	v_mul_f32_e32 v61, v61, v3
	v_mul_f32_e32 v56, v56, v6
	v_mul_f32_e32 v57, v57, v7
	v_mul_f32_e32 v52, v52, v10
	v_mul_f32_e32 v53, v53, v11
	v_mul_f32_e32 v48, v48, v112
	v_mul_f32_e32 v49, v49, v113
	v_mul_f32_e32 v46, v46, v4
	v_mul_f32_e32 v47, v47, v5
	v_mul_f32_e32 v42, v42, v8
	v_mul_f32_e32 v43, v43, v9
	v_mul_f32_e32 v38, v38, v12
	v_mul_f32_e32 v39, v39, v13
	v_mul_f32_e32 v34, v34, v114
	v_mul_f32_e32 v35, v35, v115
	v_mul_f32_e32 v44, v44, v2
	v_mul_f32_e32 v45, v45, v3
	v_mul_f32_e32 v40, v40, v6
	v_mul_f32_e32 v41, v41, v7
	v_mul_f32_e32 v36, v36, v10
	v_mul_f32_e32 v37, v37, v11
	v_mul_f32_e32 v32, v32, v112
	v_mul_f32_e32 v33, v33, v113
	v_mul_f32_e32 v30, v30, v4
	v_mul_f32_e32 v31, v31, v5
	v_mul_f32_e32 v26, v26, v8
	v_mul_f32_e32 v27, v27, v9
	v_mul_f32_e32 v22, v22, v12
	v_mul_f32_e32 v23, v23, v13
	v_mul_f32_e32 v18, v18, v114
	v_mul_f32_e32 v19, v19, v115
	v_mul_f32_e32 v28, v28, v2
	v_mul_f32_e32 v29, v29, v3
	v_mul_f32_e32 v24, v24, v6
	v_mul_f32_e32 v25, v25, v7
	v_mul_f32_e32 v20, v20, v10
	v_mul_f32_e32 v21, v21, v11
	v_mul_f32_e32 v16, v16, v112
	v_mul_f32_e32 v17, v17, v113
	s_branch .LBB0_881

.LBB0_886:
	ds_read_b64_tr_b16 v[114:115], v164 offset:0x200
	ds_read_b64_tr_b16 v[116:117], v164 offset:0xa00
	ds_read_b64_tr_b16 v[118:119], v164 offset:0x1200
	ds_read_b64_tr_b16 v[120:121], v164 offset:0x1a00
	ds_read_b64_tr_b16 v[122:123], v164 offset:0x2200
	ds_read_b64_tr_b16 v[124:125], v164 offset:0x2a00
	ds_read_b64_tr_b16 v[126:127], v164 offset:0x3200
	ds_read_b64_tr_b16 v[128:129], v164 offset:0x3a00
	s_waitcnt lgkmcnt(8)
	v_sub_f32_e32 v96, v96, v236
	v_mfma_f32_32x32x16_bf16 v[64:79], v[152:155], v[160:163], v[64:79]
	v_sub_f32_e32 v80, v80, v236
	v_exp_f32_e32 v96, v96
	v_exp_f32_e32 v80, v80
	v_mfma_f32_32x32x16_bf16 v[64:79], v[10:13], v[156:159], v[64:79]
	v_sub_f32_e32 v97, v97, v236
	v_sub_f32_e32 v81, v81, v236
	v_exp_f32_e32 v97, v97
	v_exp_f32_e32 v81, v81
	v_mfma_f32_32x32x16_bf16 v[64:79], v[6:9], v[148:151], v[64:79]
	v_sub_f32_e32 v98, v98, v236
	v_sub_f32_e32 v82, v82, v236
	v_exp_f32_e32 v98, v98
	v_exp_f32_e32 v82, v82
	v_mfma_f32_32x32x16_bf16 v[64:79], v[2:5], v[144:147], v[64:79]
	v_sub_f32_e32 v99, v99, v236
	v_sub_f32_e32 v83, v83, v236
	v_exp_f32_e32 v99, v99
	v_exp_f32_e32 v83, v83
	ds_read_b64_tr_b16 v[130:131], v164 offset:0x400
	ds_read_b64_tr_b16 v[132:133], v164 offset:0xc00
	ds_read_b64_tr_b16 v[134:135], v164 offset:0x1400
	ds_read_b64_tr_b16 v[136:137], v164 offset:0x1c00
	ds_read_b64_tr_b16 v[138:139], v164 offset:0x2400
	ds_read_b64_tr_b16 v[140:141], v164 offset:0x2c00
	ds_read_b64_tr_b16 v[142:143], v164 offset:0x3400
	ds_read_b64_tr_b16 v[144:145], v164 offset:0x3c00
	s_waitcnt lgkmcnt(8)
	s_nop 0
	v_sub_f32_e32 v100, v100, v236
	v_mfma_f32_32x32x16_bf16 v[48:63], v[152:155], v[114:117], v[48:63]
	v_sub_f32_e32 v84, v84, v236
	v_exp_f32_e32 v100, v100
	v_exp_f32_e32 v84, v84
	v_mfma_f32_32x32x16_bf16 v[48:63], v[10:13], v[118:121], v[48:63]
	v_sub_f32_e32 v101, v101, v236
	v_sub_f32_e32 v85, v85, v236
	v_exp_f32_e32 v101, v101
	v_exp_f32_e32 v85, v85
	v_mfma_f32_32x32x16_bf16 v[48:63], v[6:9], v[122:125], v[48:63]
	v_sub_f32_e32 v102, v102, v236
	v_sub_f32_e32 v86, v86, v236
	v_exp_f32_e32 v102, v102
	v_exp_f32_e32 v86, v86
	v_mfma_f32_32x32x16_bf16 v[48:63], v[2:5], v[126:129], v[48:63]
	v_sub_f32_e32 v103, v103, v236
	v_sub_f32_e32 v87, v87, v236
	v_exp_f32_e32 v103, v103
	v_exp_f32_e32 v87, v87
	ds_read_b64_tr_b16 v[114:115], v164 offset:0x600
	ds_read_b64_tr_b16 v[116:117], v164 offset:0xe00
	ds_read_b64_tr_b16 v[118:119], v164 offset:0x1600
	ds_read_b64_tr_b16 v[120:121], v164 offset:0x1e00
	ds_read_b64_tr_b16 v[122:123], v164 offset:0x2600
	ds_read_b64_tr_b16 v[124:125], v164 offset:0x2e00
	ds_read_b64_tr_b16 v[126:127], v164 offset:0x3600
	ds_read_b64_tr_b16 v[128:129], v164 offset:0x3e00
	s_waitcnt lgkmcnt(8)
	s_nop 0
	v_sub_f32_e32 v104, v104, v236
	v_mfma_f32_32x32x16_bf16 v[32:47], v[152:155], v[130:133], v[32:47]
	v_sub_f32_e32 v88, v88, v236
	v_exp_f32_e32 v104, v104
	v_exp_f32_e32 v88, v88
	v_mfma_f32_32x32x16_bf16 v[32:47], v[10:13], v[134:137], v[32:47]
	v_sub_f32_e32 v105, v105, v236
	v_sub_f32_e32 v89, v89, v236
	v_exp_f32_e32 v105, v105
	v_exp_f32_e32 v89, v89
	v_mfma_f32_32x32x16_bf16 v[32:47], v[6:9], v[138:141], v[32:47]
	v_sub_f32_e32 v106, v106, v236
	v_sub_f32_e32 v90, v90, v236
	v_exp_f32_e32 v106, v106
	v_exp_f32_e32 v90, v90
	v_mfma_f32_32x32x16_bf16 v[32:47], v[2:5], v[142:145], v[32:47]
	v_sub_f32_e32 v107, v107, v236
	v_sub_f32_e32 v91, v91, v236
	v_exp_f32_e32 v107, v107
	v_exp_f32_e32 v91, v91
	s_waitcnt lgkmcnt(0)
	s_nop 0
	v_sub_f32_e32 v108, v108, v236
	v_mfma_f32_32x32x16_bf16 v[16:31], v[152:155], v[114:117], v[16:31]
	v_sub_f32_e32 v92, v92, v236
	v_exp_f32_e32 v108, v108
	v_exp_f32_e32 v92, v92
	v_mfma_f32_32x32x16_bf16 v[16:31], v[10:13], v[118:121], v[16:31]
	v_sub_f32_e32 v109, v109, v236
	v_sub_f32_e32 v93, v93, v236
	v_exp_f32_e32 v109, v109
	v_exp_f32_e32 v93, v93
	v_mfma_f32_32x32x16_bf16 v[16:31], v[6:9], v[122:125], v[16:31]
	v_sub_f32_e32 v10, v110, v236
	v_sub_f32_e32 v11, v94, v236
	v_exp_f32_e32 v110, v10
	v_exp_f32_e32 v94, v11
	v_mfma_f32_32x32x16_bf16 v[16:31], v[2:5], v[126:129], v[16:31]
	v_sub_f32_e32 v6, v111, v236
	v_sub_f32_e32 v7, v95, v236
	v_exp_f32_e32 v111, v6
	v_exp_f32_e32 v95, v7
	v_cmp_gt_f32_e32 vcc, 1.0, v112
	s_cbranch_vccz .LBB0_890
	s_and_saveexec_b64 s[58:59], s[4:5]
	ds_write_b32 v233, v112 offset:128
	s_or_b64 exec, exec, s[58:59]
	s_waitcnt lgkmcnt(0)
	ds_read_b128 v[2:5], v232 offset:224
	ds_read_b128 v[6:9], v232 offset:192
	ds_read_b128 v[10:13], v232 offset:160
	ds_read_b128 v[114:117], v232 offset:128
	s_waitcnt lgkmcnt(3)
	v_mul_f32_e32 v78, v78, v4
	v_mul_f32_e32 v79, v79, v5
	s_waitcnt lgkmcnt(2)
	v_mul_f32_e32 v74, v74, v8
	v_mul_f32_e32 v75, v75, v9
	s_waitcnt lgkmcnt(1)
	v_mul_f32_e32 v70, v70, v12
	v_mul_f32_e32 v71, v71, v13
	s_waitcnt lgkmcnt(0)
	v_mul_f32_e32 v66, v66, v116
	v_mul_f32_e32 v67, v67, v117
	v_mul_f32_e32 v76, v76, v2
	v_mul_f32_e32 v77, v77, v3
	v_mul_f32_e32 v72, v72, v6
	v_mul_f32_e32 v73, v73, v7
	v_mul_f32_e32 v68, v68, v10
	v_mul_f32_e32 v69, v69, v11
	v_mul_f32_e32 v64, v64, v114
	v_mul_f32_e32 v65, v65, v115
	v_mul_f32_e32 v62, v62, v4
	v_mul_f32_e32 v63, v63, v5
	v_mul_f32_e32 v58, v58, v8
	v_mul_f32_e32 v59, v59, v9
	v_mul_f32_e32 v54, v54, v12
	v_mul_f32_e32 v55, v55, v13
	v_mul_f32_e32 v50, v50, v116
	v_mul_f32_e32 v51, v51, v117
	v_mul_f32_e32 v60, v60, v2
	v_mul_f32_e32 v61, v61, v3
	v_mul_f32_e32 v56, v56, v6
	v_mul_f32_e32 v57, v57, v7
	v_mul_f32_e32 v52, v52, v10
	v_mul_f32_e32 v53, v53, v11
	v_mul_f32_e32 v48, v48, v114
	v_mul_f32_e32 v49, v49, v115
	v_mul_f32_e32 v46, v46, v4
	v_mul_f32_e32 v47, v47, v5
	v_mul_f32_e32 v42, v42, v8
	v_mul_f32_e32 v43, v43, v9
	v_mul_f32_e32 v38, v38, v12
	v_mul_f32_e32 v39, v39, v13
	v_mul_f32_e32 v34, v34, v116
	v_mul_f32_e32 v35, v35, v117
	v_mul_f32_e32 v44, v44, v2
	v_mul_f32_e32 v45, v45, v3
	v_mul_f32_e32 v40, v40, v6
	v_mul_f32_e32 v41, v41, v7
	v_mul_f32_e32 v36, v36, v10
	v_mul_f32_e32 v37, v37, v11
	v_mul_f32_e32 v32, v32, v114
	v_mul_f32_e32 v33, v33, v115
	v_mul_f32_e32 v30, v30, v4
	v_mul_f32_e32 v31, v31, v5
	v_mul_f32_e32 v26, v26, v8
	v_mul_f32_e32 v27, v27, v9
	v_mul_f32_e32 v22, v22, v12
	v_mul_f32_e32 v23, v23, v13
	v_mul_f32_e32 v18, v18, v116
	v_mul_f32_e32 v19, v19, v117
	v_mul_f32_e32 v28, v28, v2
	v_mul_f32_e32 v29, v29, v3
	v_mul_f32_e32 v24, v24, v6
	v_mul_f32_e32 v25, v25, v7
	v_mul_f32_e32 v20, v20, v10
	v_mul_f32_e32 v21, v21, v11
	v_mul_f32_e32 v16, v16, v114
	v_mul_f32_e32 v17, v17, v115

.Lresc_odd_blk:
	s_and_saveexec_b64 s[54:55], s[4:5]
	ds_write_b32 v213, v225 offset:128
	s_or_b64 exec, exec, s[54:55]
	s_waitcnt lgkmcnt(0)
	ds_read_b128 v[4:7], v212 offset:224
	ds_read_b128 v[8:11], v212 offset:192
	ds_read_b128 v[12:15], v212 offset:160
	ds_read_b128 v[112:115], v212 offset:128
	s_waitcnt lgkmcnt(0)
	v_mul_f32_e32 v78, v78, v6
	v_mul_f32_e32 v79, v79, v7
	v_mul_f32_e32 v74, v74, v10
	v_mul_f32_e32 v75, v75, v11
	v_mul_f32_e32 v70, v70, v14
	v_mul_f32_e32 v71, v71, v15
	v_mul_f32_e32 v66, v66, v114
	v_mul_f32_e32 v67, v67, v115
	v_mul_f32_e32 v76, v76, v4
	v_mul_f32_e32 v77, v77, v5
	v_mul_f32_e32 v72, v72, v8
	v_mul_f32_e32 v73, v73, v9
	v_mul_f32_e32 v68, v68, v12
	v_mul_f32_e32 v69, v69, v13
	v_mul_f32_e32 v64, v64, v112
	v_mul_f32_e32 v65, v65, v113
	v_mul_f32_e32 v62, v6, v62
	v_mul_f32_e32 v63, v7, v63
	v_mul_f32_e32 v58, v10, v58
	v_mul_f32_e32 v59, v11, v59
	v_mul_f32_e32 v54, v14, v54
	v_mul_f32_e32 v55, v15, v55
	v_mul_f32_e32 v50, v114, v50
	v_mul_f32_e32 v51, v115, v51
	v_mul_f32_e32 v60, v4, v60
	v_mul_f32_e32 v61, v5, v61
	v_mul_f32_e32 v56, v8, v56
	v_mul_f32_e32 v57, v9, v57
	v_mul_f32_e32 v52, v12, v52
	v_mul_f32_e32 v53, v13, v53
	v_mul_f32_e32 v48, v112, v48
	v_mul_f32_e32 v49, v113, v49
	v_mul_f32_e32 v46, v6, v46
	v_mul_f32_e32 v47, v7, v47
	v_mul_f32_e32 v42, v10, v42
	v_mul_f32_e32 v43, v11, v43
	v_mul_f32_e32 v38, v14, v38
	v_mul_f32_e32 v39, v15, v39
	v_mul_f32_e32 v34, v114, v34
	v_mul_f32_e32 v35, v115, v35
	v_mul_f32_e32 v44, v4, v44
	v_mul_f32_e32 v45, v5, v45
	v_mul_f32_e32 v40, v8, v40
	v_mul_f32_e32 v41, v9, v41
	v_mul_f32_e32 v36, v12, v36
	v_mul_f32_e32 v37, v13, v37
	v_mul_f32_e32 v32, v112, v32
	v_mul_f32_e32 v33, v113, v33
	v_mul_f32_e32 v30, v6, v30
	v_mul_f32_e32 v31, v7, v31
	v_mul_f32_e32 v26, v10, v26
	v_mul_f32_e32 v27, v11, v27
	v_mul_f32_e32 v22, v14, v22
	v_mul_f32_e32 v23, v15, v23
	v_mul_f32_e32 v18, v114, v18
	v_mul_f32_e32 v19, v115, v19
	v_mul_f32_e32 v28, v4, v28
	v_mul_f32_e32 v29, v5, v29
	v_mul_f32_e32 v24, v8, v24
	v_mul_f32_e32 v25, v9, v25
	v_mul_f32_e32 v20, v12, v20
	v_mul_f32_e32 v21, v13, v21
	v_mul_f32_e32 v16, v112, v16
	v_mul_f32_e32 v17, v113, v17
	s_branch .LBB0_1437

.Lresc_even_blk:
	s_and_saveexec_b64 s[54:55], s[4:5]
	ds_write_b32 v213, v196 offset:128
	s_or_b64 exec, exec, s[54:55]
	s_waitcnt lgkmcnt(0)
	ds_read_b128 v[4:7], v212 offset:224
	ds_read_b128 v[8:11], v212 offset:192
	ds_read_b128 v[12:15], v212 offset:160
	ds_read_b128 v[112:115], v212 offset:128
	s_waitcnt lgkmcnt(0)
	v_mul_f32_e32 v78, v78, v6
	v_mul_f32_e32 v79, v79, v7
	v_mul_f32_e32 v74, v74, v10
	v_mul_f32_e32 v75, v75, v11
	v_mul_f32_e32 v70, v70, v14
	v_mul_f32_e32 v71, v71, v15
	v_mul_f32_e32 v66, v66, v114
	v_mul_f32_e32 v67, v67, v115
	v_mul_f32_e32 v76, v76, v4
	v_mul_f32_e32 v77, v77, v5
	v_mul_f32_e32 v72, v72, v8
	v_mul_f32_e32 v73, v73, v9
	v_mul_f32_e32 v68, v68, v12
	v_mul_f32_e32 v69, v69, v13
	v_mul_f32_e32 v64, v64, v112
	v_mul_f32_e32 v65, v65, v113
	v_mul_f32_e32 v62, v6, v62
	v_mul_f32_e32 v63, v7, v63
	v_mul_f32_e32 v58, v10, v58
	v_mul_f32_e32 v59, v11, v59
	v_mul_f32_e32 v54, v14, v54
	v_mul_f32_e32 v55, v15, v55
	v_mul_f32_e32 v50, v114, v50
	v_mul_f32_e32 v51, v115, v51
	v_mul_f32_e32 v60, v4, v60
	v_mul_f32_e32 v61, v5, v61
	v_mul_f32_e32 v56, v8, v56
	v_mul_f32_e32 v57, v9, v57
	v_mul_f32_e32 v52, v12, v52
	v_mul_f32_e32 v53, v13, v53
	v_mul_f32_e32 v48, v112, v48
	v_mul_f32_e32 v49, v113, v49
	v_mul_f32_e32 v46, v6, v46
	v_mul_f32_e32 v47, v7, v47
	v_mul_f32_e32 v42, v10, v42
	v_mul_f32_e32 v43, v11, v43
	v_mul_f32_e32 v38, v14, v38
	v_mul_f32_e32 v39, v15, v39
	v_mul_f32_e32 v34, v114, v34
	v_mul_f32_e32 v35, v115, v35
	v_mul_f32_e32 v44, v4, v44
	v_mul_f32_e32 v45, v5, v45
	v_mul_f32_e32 v40, v8, v40
	v_mul_f32_e32 v41, v9, v41
	v_mul_f32_e32 v36, v12, v36
	v_mul_f32_e32 v37, v13, v37
	v_mul_f32_e32 v32, v112, v32
	v_mul_f32_e32 v33, v113, v33
	v_mul_f32_e32 v30, v6, v30
	v_mul_f32_e32 v31, v7, v31
	v_mul_f32_e32 v26, v10, v26
	v_mul_f32_e32 v27, v11, v27
	v_mul_f32_e32 v22, v14, v22
	v_mul_f32_e32 v23, v15, v23
	v_mul_f32_e32 v18, v114, v18
	v_mul_f32_e32 v19, v115, v19
	v_mul_f32_e32 v28, v4, v28
	v_mul_f32_e32 v29, v5, v29
	v_mul_f32_e32 v24, v8, v24
	v_mul_f32_e32 v25, v9, v25
	v_mul_f32_e32 v20, v12, v20
	v_mul_f32_e32 v21, v13, v21
	v_mul_f32_e32 v16, v112, v16
	v_mul_f32_e32 v17, v113, v17
	s_branch .LBB0_1452

.LBB0_1469:
	ds_read_b64_tr_b16 v[114:115], v165 offset:0x200
	ds_read_b64_tr_b16 v[116:117], v165 offset:0xa00
	ds_read_b64_tr_b16 v[118:119], v165 offset:0x1200
	ds_read_b64_tr_b16 v[120:121], v165 offset:0x1a00
	ds_read_b64_tr_b16 v[122:123], v165 offset:0x2200
	ds_read_b64_tr_b16 v[124:125], v165 offset:0x2a00
	ds_read_b64_tr_b16 v[130:131], v165 offset:0x3200
	ds_read_b64_tr_b16 v[132:133], v165 offset:0x3a00
	s_waitcnt lgkmcnt(8)
	v_exp_f32_e32 v96, v128
	v_mfma_f32_32x32x16_bf16 v[64:79], v[144:147], v[160:163], v[64:79]
	v_exp_f32_e32 v80, v112
	v_mfma_f32_32x32x16_bf16 v[64:79], v[12:15], v[156:159], v[64:79]
	v_exp_f32_e32 v97, v97
	v_exp_f32_e32 v81, v81
	v_mfma_f32_32x32x16_bf16 v[64:79], v[8:11], v[152:155], v[64:79]
	v_exp_f32_e32 v98, v98
	v_exp_f32_e32 v82, v82
	v_mfma_f32_32x32x16_bf16 v[64:79], v[4:7], v[148:151], v[64:79]
	v_exp_f32_e32 v99, v99
	v_exp_f32_e32 v83, v83
	ds_read_b64_tr_b16 v[126:127], v165 offset:0x400
	ds_read_b64_tr_b16 v[128:129], v165 offset:0xc00
	ds_read_b64_tr_b16 v[134:135], v165 offset:0x1400
	ds_read_b64_tr_b16 v[136:137], v165 offset:0x1c00
	ds_read_b64_tr_b16 v[138:139], v165 offset:0x2400
	ds_read_b64_tr_b16 v[140:141], v165 offset:0x2c00
	ds_read_b64_tr_b16 v[148:149], v165 offset:0x3400
	ds_read_b64_tr_b16 v[150:151], v165 offset:0x3c00
	s_waitcnt lgkmcnt(8)
	s_nop 0
	v_exp_f32_e32 v100, v100
	v_mfma_f32_32x32x16_bf16 v[48:63], v[144:147], v[114:117], v[48:63]
	v_exp_f32_e32 v84, v84
	v_mfma_f32_32x32x16_bf16 v[48:63], v[12:15], v[118:121], v[48:63]
	v_exp_f32_e32 v101, v101
	v_exp_f32_e32 v85, v85
	v_mfma_f32_32x32x16_bf16 v[48:63], v[8:11], v[122:125], v[48:63]
	v_exp_f32_e32 v102, v102
	v_exp_f32_e32 v86, v86
	v_mfma_f32_32x32x16_bf16 v[48:63], v[4:7], v[130:133], v[48:63]
	v_exp_f32_e32 v103, v103
	v_exp_f32_e32 v87, v87
	ds_read_b64_tr_b16 v[112:113], v165 offset:0x600
	ds_read_b64_tr_b16 v[114:115], v165 offset:0xe00
	ds_read_b64_tr_b16 v[116:117], v165 offset:0x1600
	ds_read_b64_tr_b16 v[118:119], v165 offset:0x1e00
	ds_read_b64_tr_b16 v[120:121], v165 offset:0x2600
	ds_read_b64_tr_b16 v[122:123], v165 offset:0x2e00
	ds_read_b64_tr_b16 v[130:131], v165 offset:0x3600
	ds_read_b64_tr_b16 v[132:133], v165 offset:0x3e00
	s_waitcnt lgkmcnt(8)
	s_nop 0
	v_exp_f32_e32 v104, v104
	v_mfma_f32_32x32x16_bf16 v[32:47], v[144:147], v[126:129], v[32:47]
	v_exp_f32_e32 v88, v88
	v_mfma_f32_32x32x16_bf16 v[32:47], v[12:15], v[134:137], v[32:47]
	v_exp_f32_e32 v105, v105
	v_exp_f32_e32 v89, v89
	v_mfma_f32_32x32x16_bf16 v[32:47], v[8:11], v[138:141], v[32:47]
	v_exp_f32_e32 v106, v106
	v_exp_f32_e32 v90, v90
	v_mfma_f32_32x32x16_bf16 v[32:47], v[4:7], v[148:151], v[32:47]
	v_exp_f32_e32 v107, v107
	v_exp_f32_e32 v91, v91
	s_waitcnt lgkmcnt(0)
	s_nop 0
	v_exp_f32_e32 v108, v108
	v_mfma_f32_32x32x16_bf16 v[16:31], v[144:147], v[112:115], v[16:31]
	v_exp_f32_e32 v92, v92
	v_mfma_f32_32x32x16_bf16 v[16:31], v[12:15], v[116:119], v[16:31]
	v_exp_f32_e32 v109, v109
	v_exp_f32_e32 v93, v93
	v_mfma_f32_32x32x16_bf16 v[16:31], v[8:11], v[120:123], v[16:31]
	v_exp_f32_e32 v110, v110
	v_exp_f32_e32 v94, v94
	v_mfma_f32_32x32x16_bf16 v[16:31], v[4:7], v[130:133], v[16:31]
	v_exp_f32_e32 v111, v111
	v_exp_f32_e32 v95, v95
	v_cmp_gt_f32_e32 vcc, 1.0, v0
	s_cbranch_vccz .LBB0_1473
	s_and_saveexec_b64 s[52:53], s[4:5]
	ds_write_b32 v213, v0 offset:128
	s_or_b64 exec, exec, s[52:53]
	s_waitcnt lgkmcnt(0)
	ds_read_b128 v[4:7], v212 offset:224
	ds_read_b128 v[8:11], v212 offset:192
	ds_read_b128 v[12:15], v212 offset:160
	ds_read_b128 v[112:115], v212 offset:128
	s_waitcnt lgkmcnt(3)
	v_mul_f32_e32 v78, v78, v6
	v_mul_f32_e32 v79, v79, v7
	s_waitcnt lgkmcnt(2)
	v_mul_f32_e32 v74, v74, v10
	v_mul_f32_e32 v75, v75, v11
	s_waitcnt lgkmcnt(1)
	v_mul_f32_e32 v70, v70, v14
	v_mul_f32_e32 v71, v71, v15
	s_waitcnt lgkmcnt(0)
	v_mul_f32_e32 v66, v66, v114
	v_mul_f32_e32 v67, v67, v115
	v_mul_f32_e32 v76, v76, v4
	v_mul_f32_e32 v77, v77, v5
	v_mul_f32_e32 v72, v72, v8
	v_mul_f32_e32 v73, v73, v9
	v_mul_f32_e32 v68, v68, v12
	v_mul_f32_e32 v69, v69, v13
	v_mul_f32_e32 v64, v64, v112
	v_mul_f32_e32 v65, v65, v113
	v_mul_f32_e32 v62, v6, v62
	v_mul_f32_e32 v63, v7, v63
	v_mul_f32_e32 v58, v10, v58
	v_mul_f32_e32 v59, v11, v59
	v_mul_f32_e32 v54, v14, v54
	v_mul_f32_e32 v55, v15, v55
	v_mul_f32_e32 v50, v114, v50
	v_mul_f32_e32 v51, v115, v51
	v_mul_f32_e32 v60, v4, v60
	v_mul_f32_e32 v61, v5, v61
	v_mul_f32_e32 v56, v8, v56
	v_mul_f32_e32 v57, v9, v57
	v_mul_f32_e32 v52, v12, v52
	v_mul_f32_e32 v53, v13, v53
	v_mul_f32_e32 v48, v112, v48
	v_mul_f32_e32 v49, v113, v49
	v_mul_f32_e32 v46, v6, v46
	v_mul_f32_e32 v47, v7, v47
	v_mul_f32_e32 v42, v10, v42
	v_mul_f32_e32 v43, v11, v43
	v_mul_f32_e32 v38, v14, v38
	v_mul_f32_e32 v39, v15, v39
	v_mul_f32_e32 v34, v114, v34
	v_mul_f32_e32 v35, v115, v35
	v_mul_f32_e32 v44, v4, v44
	v_mul_f32_e32 v45, v5, v45
	v_mul_f32_e32 v40, v8, v40
	v_mul_f32_e32 v41, v9, v41
	v_mul_f32_e32 v36, v12, v36
	v_mul_f32_e32 v37, v13, v37
	v_mul_f32_e32 v32, v112, v32
	v_mul_f32_e32 v33, v113, v33
	v_mul_f32_e32 v30, v6, v30
	v_mul_f32_e32 v31, v7, v31
	v_mul_f32_e32 v26, v10, v26
	v_mul_f32_e32 v27, v11, v27
	v_mul_f32_e32 v22, v14, v22
	v_mul_f32_e32 v23, v15, v23
	v_mul_f32_e32 v18, v114, v18
	v_mul_f32_e32 v19, v115, v19
	v_mul_f32_e32 v28, v4, v28
	v_mul_f32_e32 v29, v5, v29
	v_mul_f32_e32 v24, v8, v24
	v_mul_f32_e32 v25, v9, v25
	v_mul_f32_e32 v20, v12, v20
	v_mul_f32_e32 v21, v13, v21
	v_mul_f32_e32 v16, v112, v16
	v_mul_f32_e32 v17, v113, v17
